# v48 + s_setprio 1 for odd waves during the attention phase (tests wave-to-SIMD pairing; de-phase the two waves of a SIMD)
# speedup vs baseline: 1.0004x; 1.0004x over previous
; #define LAS __attribute__((address_space(3)))
; __device__ __forceinline__ void phase_attn(const Params& p, unsigned char* lds, LAS unsigned char* lds3) {
;     for (int u = blockIdx.x; u < 2048; u += gridDim.x) {
;         const int bx = u & 255, i = u >> 8; const int wv = (bx & 7) * 32 + (bx >> 3);
;         const int combo = wv >> 2, quarter = wv & 3; const int k = i & 3;
;         const int b = combo >> 3, h = ((combo & 7) + 2 * k + (i >> 2)) & 7;
;         const int qb = (k == 0) ? quarter : (k == 1) ? 15 - quarter : (k == 2) ? 7 - quarter : 8 + quarter;
;         if (i < 4) attn_unit<false>(lds, lds3, p, b, h, qb); else attn_unit<true>(lds, lds3, p, b, h, qb);
;     }
;     __syncthreads();
; }
.LBB0_356:
	s_andn2_b64 vcc, exec, s[0:1]
	s_cbranch_vccnz .LBB0_617
	v_readfirstlane_b32 s100, v174
	s_nop 3
	s_bitcmp1_b32 s100, 6
	s_cbranch_scc0 .Lattn_noprio
	s_setprio 1
